# GDN scan compute waves: state decay multiplies hoisted into the MFMA-paced first half of each chunk
# speedup vs baseline: 1.0053x; 1.0007x over previous
.LBB0_988:
	v_lshl_add_u64 v[64:65], s[30:31], 0, v[162:163]
	v_lshl_add_u64 v[66:67], s[30:31], 0, v[160:161]
	v_lshl_add_u64 v[68:69], s[30:31], 0, v[158:159]
	v_lshl_add_u64 v[70:71], s[30:31], 0, v[156:157]
	global_load_dwordx2 v[198:199], v[64:65], off
	global_load_dwordx2 v[194:195], v[66:67], off
	global_load_dwordx2 v[190:191], v[68:69], off
	global_load_dwordx2 v[180:181], v[70:71], off
	v_lshl_add_u64 v[64:65], s[30:31], 0, v[154:155]
	v_lshl_add_u64 v[66:67], s[30:31], 0, v[152:153]
	v_lshl_add_u64 v[68:69], s[30:31], 0, v[150:151]
	v_lshl_add_u64 v[70:71], s[30:31], 0, v[148:149]
	global_load_dwordx2 v[196:197], v[64:65], off
	global_load_dwordx2 v[192:193], v[66:67], off
	global_load_dwordx2 v[188:189], v[68:69], off
	global_load_dwordx2 v[186:187], v[70:71], off
	s_add_i32 s2, s1, 1
	ds_read_b128 v[92:95], v101 offset:16384
	ds_read_b128 v[102:105], v101 offset:17408
	ds_read_b128 v[106:109], v101 offset:18432
	ds_read_b128 v[110:113], v101 offset:19456
	ds_read_b128 v[118:121], v101 offset:20480
	ds_read_b128 v[122:125], v101 offset:21504
	ds_read_b128 v[126:129], v101 offset:22528
	ds_read_b128 v[130:133], v101 offset:23552
	v_cvt_pk_bf16_f32 v64, v0, v1
	v_cvt_pk_bf16_f32 v65, v2, v3
	v_cvt_pk_bf16_f32 v66, v4, v5
	v_cvt_pk_bf16_f32 v67, v6, v7
	v_cvt_pk_bf16_f32 v68, v8, v9
	v_cvt_pk_bf16_f32 v69, v10, v11
	v_cvt_pk_bf16_f32 v70, v12, v13
	v_cvt_pk_bf16_f32 v71, v14, v15
	v_cvt_pk_bf16_f32 v72, v16, v17
	v_cvt_pk_bf16_f32 v73, v18, v19
	v_cvt_pk_bf16_f32 v74, v24, v25
	v_cvt_pk_bf16_f32 v75, v26, v27
	v_cvt_pk_bf16_f32 v76, v32, v33
	v_cvt_pk_bf16_f32 v77, v34, v35
	v_cvt_pk_bf16_f32 v78, v40, v41
	v_cvt_pk_bf16_f32 v79, v42, v43
	v_cvt_pk_bf16_f32 v80, v20, v21
	v_cvt_pk_bf16_f32 v81, v22, v23
	v_cvt_pk_bf16_f32 v82, v28, v29
	v_cvt_pk_bf16_f32 v83, v30, v31
	v_cvt_pk_bf16_f32 v84, v36, v37
	v_cvt_pk_bf16_f32 v85, v38, v39
	v_cvt_pk_bf16_f32 v86, v44, v45
	v_cvt_pk_bf16_f32 v87, v46, v47
	v_cvt_pk_bf16_f32 v88, v48, v49
	v_cvt_pk_bf16_f32 v89, v50, v51
	v_cvt_pk_bf16_f32 v90, v52, v53
	v_cvt_pk_bf16_f32 v91, v54, v55
	v_cvt_pk_bf16_f32 v114, v56, v57
	v_cvt_pk_bf16_f32 v115, v58, v59
	v_cvt_pk_bf16_f32 v116, v60, v61
	v_cvt_pk_bf16_f32 v117, v62, v63
	v_readlane_b32 s0, v96, s1
	s_waitcnt lgkmcnt(7)
	v_mfma_f32_16x16x32_bf16 v[204:207], v[92:95], v[64:67], 0
	v_mfma_f32_16x16x32_bf16 v[92:95], v[92:95], v[80:83], 0
	s_waitcnt lgkmcnt(6)
	v_mfma_f32_16x16x32_bf16 v[204:207], v[102:105], v[68:71], v[204:207]
	v_mfma_f32_16x16x32_bf16 v[92:95], v[102:105], v[84:87], v[92:95]
	s_waitcnt lgkmcnt(5)
	v_mfma_f32_16x16x32_bf16 v[102:105], v[106:109], v[72:75], v[204:207]
	v_mfma_f32_16x16x32_bf16 v[106:109], v[106:109], v[88:91], v[92:95]
	s_waitcnt lgkmcnt(4)
	v_mfma_f32_16x16x32_bf16 v[92:95], v[110:113], v[76:79], v[102:105]
	v_mfma_f32_16x16x32_bf16 v[102:105], v[110:113], v[114:117], v[106:109]
	v_pk_mul_f32 v[2:3], v[2:3], s[0:1] op_sel_hi:[1,0]
	v_pk_mul_f32 v[0:1], v[0:1], s[0:1] op_sel_hi:[1,0]
	v_pk_mul_f32 v[22:23], v[22:23], s[0:1] op_sel_hi:[1,0]
	v_pk_mul_f32 v[20:21], v[20:21], s[0:1] op_sel_hi:[1,0]
	v_pk_mul_f32 v[6:7], v[6:7], s[0:1] op_sel_hi:[1,0]
	s_nop 0
	ds_read_b128 v[204:207], v101 offset:24576
	ds_read_b128 v[208:211], v101 offset:25600
	ds_read_b128 v[212:215], v101 offset:26624
	ds_read_b128 v[216:219], v101 offset:27648
	s_waitcnt lgkmcnt(7)
	v_mfma_f32_16x16x32_bf16 v[106:109], v[118:121], v[64:67], 0
	v_mfma_f32_16x16x32_bf16 v[110:113], v[118:121], v[80:83], 0
	s_waitcnt lgkmcnt(6)
	v_mfma_f32_16x16x32_bf16 v[106:109], v[122:125], v[68:71], v[106:109]
	v_mfma_f32_16x16x32_bf16 v[110:113], v[122:125], v[84:87], v[110:113]
	s_waitcnt lgkmcnt(5)
	v_mfma_f32_16x16x32_bf16 v[106:109], v[126:129], v[72:75], v[106:109]
	v_mfma_f32_16x16x32_bf16 v[110:113], v[126:129], v[88:91], v[110:113]
	s_waitcnt lgkmcnt(4)
	v_mfma_f32_16x16x32_bf16 v[106:109], v[130:133], v[76:79], v[106:109]
	v_mfma_f32_16x16x32_bf16 v[110:113], v[130:133], v[114:117], v[110:113]
	v_pk_mul_f32 v[4:5], v[4:5], s[0:1] op_sel_hi:[1,0]
	v_pk_mul_f32 v[30:31], v[30:31], s[0:1] op_sel_hi:[1,0]
	v_pk_mul_f32 v[28:29], v[28:29], s[0:1] op_sel_hi:[1,0]
	v_pk_mul_f32 v[10:11], v[10:11], s[0:1] op_sel_hi:[1,0]
	ds_read_b128 v[126:129], v101 offset:28672
	ds_read_b128 v[130:133], v101 offset:29696
	ds_read_b128 v[220:223], v101 offset:30720
	ds_read_b128 v[234:237], v101 offset:31744
	s_waitcnt lgkmcnt(7)
	v_mfma_f32_16x16x32_bf16 v[118:121], v[204:207], v[64:67], 0
	v_mfma_f32_16x16x32_bf16 v[122:125], v[204:207], v[80:83], 0
	s_waitcnt lgkmcnt(6)
	v_mfma_f32_16x16x32_bf16 v[118:121], v[208:211], v[68:71], v[118:121]
	v_mfma_f32_16x16x32_bf16 v[122:125], v[208:211], v[84:87], v[122:125]
	s_waitcnt lgkmcnt(5)
	v_mfma_f32_16x16x32_bf16 v[118:121], v[212:215], v[72:75], v[118:121]
	v_mfma_f32_16x16x32_bf16 v[122:125], v[212:215], v[88:91], v[122:125]
	s_waitcnt lgkmcnt(4)
	v_mfma_f32_16x16x32_bf16 v[118:121], v[216:219], v[76:79], v[118:121]
	v_mfma_f32_16x16x32_bf16 v[122:125], v[216:219], v[114:117], v[122:125]
	v_pk_mul_f32 v[8:9], v[8:9], s[0:1] op_sel_hi:[1,0]
	v_pk_mul_f32 v[38:39], v[38:39], s[0:1] op_sel_hi:[1,0]
	v_pk_mul_f32 v[36:37], v[36:37], s[0:1] op_sel_hi:[1,0]
	v_pk_mul_f32 v[14:15], v[14:15], s[0:1] op_sel_hi:[1,0]
	ds_read_b128 v[204:207], v101
	ds_read_b128 v[208:211], v101 offset:1024
	ds_read_b128 v[212:215], v101 offset:2048
	ds_read_b128 v[216:219], v101 offset:3072
	s_waitcnt lgkmcnt(7)
	v_mfma_f32_16x16x32_bf16 v[238:241], v[126:129], v[64:67], 0
	v_mfma_f32_16x16x32_bf16 v[126:129], v[126:129], v[80:83], 0
	s_waitcnt lgkmcnt(6)
	v_mfma_f32_16x16x32_bf16 v[238:241], v[130:133], v[68:71], v[238:241]
	v_mfma_f32_16x16x32_bf16 v[126:129], v[130:133], v[84:87], v[126:129]
	s_waitcnt lgkmcnt(5)
	v_mfma_f32_16x16x32_bf16 v[130:133], v[220:223], v[72:75], v[238:241]
	v_mfma_f32_16x16x32_bf16 v[220:223], v[220:223], v[88:91], v[126:129]
	s_waitcnt lgkmcnt(4)
	v_mfma_f32_16x16x32_bf16 v[126:129], v[234:237], v[76:79], v[130:133]
	v_mfma_f32_16x16x32_bf16 v[130:133], v[234:237], v[114:117], v[220:223]
	v_pk_mul_f32 v[12:13], v[12:13], s[0:1] op_sel_hi:[1,0]
	v_pk_mul_f32 v[46:47], v[46:47], s[0:1] op_sel_hi:[1,0]
	v_pk_mul_f32 v[44:45], v[44:45], s[0:1] op_sel_hi:[1,0]
	v_pk_mul_f32 v[18:19], v[18:19], s[0:1] op_sel_hi:[1,0]
	s_nop 4
	ds_read_b128 v[220:223], v101 offset:4096
	ds_read_b128 v[234:237], v101 offset:5120
	ds_read_b128 v[238:241], v101 offset:6144
	ds_read_b128 v[242:245], v101 offset:7168
	s_waitcnt lgkmcnt(7)
	v_mfma_f32_16x16x32_bf16 v[246:249], v[204:207], v[64:67], 0
	s_waitcnt vmcnt(15)
	v_lshlrev_b32_e32 v203, 16, v178
	v_and_b32_e32 v178, 0xffff0000, v178
	v_mfma_f32_16x16x32_bf16 v[204:207], v[204:207], v[80:83], 0
	s_waitcnt lgkmcnt(6)
	v_mfma_f32_16x16x32_bf16 v[246:249], v[208:211], v[68:71], v[246:249]
	v_mfma_f32_16x16x32_bf16 v[204:207], v[208:211], v[84:87], v[204:207]
	s_waitcnt lgkmcnt(5)
	v_mfma_f32_16x16x32_bf16 v[208:211], v[212:215], v[72:75], v[246:249]
	v_mfma_f32_16x16x32_bf16 v[204:207], v[212:215], v[88:91], v[204:207]
	v_lshlrev_b32_e32 v212, 16, v179
	v_and_b32_e32 v179, 0xffff0000, v179
	s_waitcnt lgkmcnt(4)
	v_mfma_f32_16x16x32_bf16 v[208:211], v[216:219], v[76:79], v[208:211]
	v_mfma_f32_16x16x32_bf16 v[204:207], v[216:219], v[114:117], v[204:207]
	v_pk_mul_f32 v[16:17], v[16:17], s[0:1] op_sel_hi:[1,0]
	v_pk_mul_f32 v[50:51], v[50:51], s[0:1] op_sel_hi:[1,0]
	v_pk_mul_f32 v[48:49], v[48:49], s[0:1] op_sel_hi:[1,0]
	v_pk_mul_f32 v[26:27], v[26:27], s[0:1] op_sel_hi:[1,0]
	s_nop 6
	v_sub_f32_e32 v224, v179, v211
	v_sub_f32_e32 v233, v178, v209
	s_waitcnt vmcnt(11)
	v_lshlrev_b32_e32 v178, 16, v176
	v_and_b32_e32 v176, 0xffff0000, v176
	v_lshlrev_b32_e32 v179, 16, v177
	v_and_b32_e32 v177, 0xffff0000, v177
	v_sub_f32_e32 v225, v212, v210
	v_sub_f32_e32 v203, v203, v208
	v_sub_f32_e32 v246, v177, v207
	v_sub_f32_e32 v247, v179, v206
	v_sub_f32_e32 v248, v176, v205
	v_sub_f32_e32 v249, v178, v204
	ds_read_b128 v[176:179], v101 offset:8192
	ds_read_b128 v[204:207], v101 offset:9216
	ds_read_b128 v[208:211], v101 offset:10240
	ds_read_b128 v[212:215], v101 offset:11264
	s_waitcnt lgkmcnt(7)
	v_mfma_f32_16x16x32_bf16 v[216:219], v[220:223], v[64:67], 0
	v_mfma_f32_16x16x32_bf16 v[220:223], v[220:223], v[80:83], 0
	s_waitcnt lgkmcnt(6)
	v_mfma_f32_16x16x32_bf16 v[216:219], v[234:237], v[68:71], v[216:219]
	v_mfma_f32_16x16x32_bf16 v[220:223], v[234:237], v[84:87], v[220:223]
	v_lshlrev_b32_e32 v234, 16, v174
	v_and_b32_e32 v174, 0xffff0000, v174
	v_lshlrev_b32_e32 v235, 16, v175
	s_waitcnt lgkmcnt(5)
	v_mfma_f32_16x16x32_bf16 v[216:219], v[238:241], v[72:75], v[216:219]
	v_and_b32_e32 v175, 0xffff0000, v175
	v_mfma_f32_16x16x32_bf16 v[220:223], v[238:241], v[88:91], v[220:223]
	s_waitcnt lgkmcnt(4)
	v_mfma_f32_16x16x32_bf16 v[216:219], v[242:245], v[76:79], v[216:219]
	v_mfma_f32_16x16x32_bf16 v[220:223], v[242:245], v[114:117], v[220:223]
	v_pk_mul_f32 v[24:25], v[24:25], s[0:1] op_sel_hi:[1,0]
	v_pk_mul_f32 v[54:55], v[54:55], s[0:1] op_sel_hi:[1,0]
	v_pk_mul_f32 v[52:53], v[52:53], s[0:1] op_sel_hi:[1,0]
	v_pk_mul_f32 v[34:35], v[34:35], s[0:1] op_sel_hi:[1,0]
	s_nop 6
	v_sub_f32_e32 v242, v175, v219
	v_sub_f32_e32 v244, v174, v217
	s_waitcnt vmcnt(10)
	v_lshlrev_b32_e32 v174, 16, v172
	v_and_b32_e32 v172, 0xffff0000, v172
	v_lshlrev_b32_e32 v175, 16, v173
	v_and_b32_e32 v173, 0xffff0000, v173
	v_sub_f32_e32 v243, v235, v218
	v_sub_f32_e32 v245, v234, v216
	v_sub_f32_e32 v250, v173, v223
	v_sub_f32_e32 v251, v175, v222
	v_sub_f32_e32 v227, v172, v221
	v_sub_f32_e32 v182, v174, v220
	ds_read_b128 v[172:175], v101 offset:12288
	ds_read_b128 v[216:219], v101 offset:13312
	ds_read_b128 v[220:223], v101 offset:14336
	ds_read_b128 v[234:237], v101 offset:15360
	s_waitcnt lgkmcnt(7)
	v_mfma_f32_16x16x32_bf16 v[238:241], v[176:179], v[64:67], 0
	v_lshlrev_b32_e32 v183, 16, v170
	v_and_b32_e32 v170, 0xffff0000, v170
	v_mfma_f32_16x16x32_bf16 v[176:179], v[176:179], v[80:83], 0
	s_waitcnt lgkmcnt(6)
	v_mfma_f32_16x16x32_bf16 v[238:241], v[204:207], v[68:71], v[238:241]
	v_mfma_f32_16x16x32_bf16 v[176:179], v[204:207], v[84:87], v[176:179]
	s_waitcnt lgkmcnt(5)
	v_mfma_f32_16x16x32_bf16 v[204:207], v[208:211], v[72:75], v[238:241]
	v_mfma_f32_16x16x32_bf16 v[176:179], v[208:211], v[88:91], v[176:179]
	v_lshlrev_b32_e32 v208, 16, v171
	v_and_b32_e32 v171, 0xffff0000, v171
	s_waitcnt lgkmcnt(4)
	v_mfma_f32_16x16x32_bf16 v[204:207], v[212:215], v[76:79], v[204:207]
	v_mfma_f32_16x16x32_bf16 v[176:179], v[212:215], v[114:117], v[176:179]
	v_pk_mul_f32 v[32:33], v[32:33], s[0:1] op_sel_hi:[1,0]
	v_pk_mul_f32 v[58:59], v[58:59], s[0:1] op_sel_hi:[1,0]
	v_pk_mul_f32 v[56:57], v[56:57], s[0:1] op_sel_hi:[1,0]
	v_mul_f32_e64 v42, v42, s0
	s_nop 6
	v_sub_f32_e32 v207, v171, v207
	v_sub_f32_e32 v205, v170, v205
	s_waitcnt vmcnt(9)
	v_lshlrev_b32_e32 v170, 16, v168
	v_and_b32_e32 v168, 0xffff0000, v168
	v_lshlrev_b32_e32 v171, 16, v169
	v_and_b32_e32 v169, 0xffff0000, v169
	v_sub_f32_e32 v206, v208, v206
	v_sub_f32_e32 v183, v183, v204
	v_sub_f32_e32 v204, v169, v179
	v_sub_f32_e32 v208, v171, v178
	v_sub_f32_e32 v209, v168, v177
	v_sub_f32_e32 v210, v170, v176
	ds_read_b128 v[168:171], v101 offset:49152
	ds_read_b128 v[176:179], v101 offset:50176
	s_waitcnt lgkmcnt(5)
	v_mfma_f32_16x16x32_bf16 v[64:67], v[172:175], v[64:67], 0
	s_waitcnt lgkmcnt(4)
	v_mfma_f32_16x16x32_bf16 v[64:67], v[216:219], v[68:71], v[64:67]
	v_lshlrev_b32_e32 v68, 16, v165
	v_and_b32_e32 v69, 0xffff0000, v165
	v_lshlrev_b32_e32 v70, 16, v164
	s_waitcnt lgkmcnt(3)
	v_mfma_f32_16x16x32_bf16 v[64:67], v[220:223], v[72:75], v[64:67]
	v_and_b32_e32 v71, 0xffff0000, v164
	s_waitcnt vmcnt(8)
	v_lshlrev_b32_e32 v74, 16, v166
	v_and_b32_e32 v75, 0xffff0000, v167
	v_mfma_f32_16x16x32_bf16 v[80:83], v[172:175], v[80:83], 0
	s_waitcnt lgkmcnt(2)
	v_mfma_f32_16x16x32_bf16 v[64:67], v[234:237], v[76:79], v[64:67]
	v_cvt_pk_bf16_f32 v76, v210, v209
	v_cvt_pk_bf16_f32 v77, v208, v204
	s_nop 5
	v_sub_f32_e32 v72, v69, v67
	v_sub_f32_e32 v73, v68, v66
	v_mfma_f32_16x16x32_bf16 v[66:69], v[216:219], v[84:87], v[80:83]
	v_sub_f32_e32 v71, v71, v65
	v_sub_f32_e32 v70, v70, v64
	v_cvt_pk_bf16_f32 v70, v70, v71
	v_mfma_f32_16x16x32_bf16 v[64:67], v[220:223], v[88:91], v[66:69]
	v_cvt_pk_bf16_f32 v71, v73, v72
	v_cvt_pk_bf16_f32 v72, v249, v248
	v_cvt_pk_bf16_f32 v73, v247, v246
	v_mfma_f32_16x16x32_bf16 v[64:67], v[234:237], v[114:117], v[64:67]
	v_mul_f32_e64 v43, v43, s0
	v_pk_mul_f32 v[40:41], v[40:41], s[0:1] op_sel_hi:[1,0]
	v_pk_mul_f32 v[62:63], v[62:63], s[0:1] op_sel_hi:[1,0]
	v_pk_mul_f32 v[60:61], v[60:61], s[0:1] op_sel_hi:[1,0]
	v_and_b32_e32 v68, 0xffff0000, v166
	v_lshlrev_b32_e32 v69, 16, v167
	s_nop 5
	v_sub_f32_e32 v79, v75, v67
	v_sub_f32_e32 v80, v69, v66
	v_sub_f32_e32 v78, v68, v65
	v_sub_f32_e32 v81, v74, v64
	v_cvt_pk_bf16_f32 v64, v203, v233
	v_cvt_pk_bf16_f32 v65, v225, v224
	v_cvt_pk_bf16_f32 v66, v245, v244
	v_cvt_pk_bf16_f32 v67, v243, v242
	v_cvt_pk_bf16_f32 v68, v183, v205
	v_cvt_pk_bf16_f32 v69, v206, v207
	v_cvt_pk_bf16_f32 v74, v182, v227
	v_cvt_pk_bf16_f32 v75, v251, v250
	v_cvt_pk_bf16_f32 v78, v81, v78
	v_cvt_pk_bf16_f32 v79, v80, v79
	ds_read_b128 v[80:83], v101 offset:51200
	ds_read_b128 v[84:87], v101 offset:52224
	ds_read_b128 v[204:207], v101 offset:53248
	ds_read_b128 v[208:211], v101 offset:54272
	s_waitcnt lgkmcnt(5)
	v_mfma_f32_16x16x32_bf16 v[88:91], v[168:171], v[64:67], v[92:95]
	v_mfma_f32_16x16x32_bf16 v[92:95], v[168:171], v[72:75], v[102:105]
	s_waitcnt lgkmcnt(4)
	v_mfma_f32_16x16x32_bf16 v[88:91], v[176:179], v[68:71], v[88:91]
	v_mfma_f32_16x16x32_bf16 v[92:95], v[176:179], v[76:79], v[92:95]
	ds_read_b128 v[212:215], v101 offset:55296
	ds_read_b128 v[216:219], v101 offset:56320
	s_waitcnt lgkmcnt(5)
	v_mfma_f32_16x16x32_bf16 v[106:109], v[80:83], v[64:67], v[106:109]
	v_mfma_f32_16x16x32_bf16 v[80:83], v[80:83], v[72:75], v[110:113]
	s_waitcnt lgkmcnt(4)
	v_mfma_f32_16x16x32_bf16 v[106:109], v[84:87], v[68:71], v[106:109]
	v_mfma_f32_16x16x32_bf16 v[80:83], v[84:87], v[76:79], v[80:83]
	ds_read_b128 v[220:223], v101 offset:32768
	ds_read_b128 v[234:237], v101 offset:33792
	s_waitcnt lgkmcnt(5)
	v_mfma_f32_16x16x32_bf16 v[118:121], v[204:207], v[64:67], v[118:121]
	v_mfma_f32_16x16x32_bf16 v[102:105], v[204:207], v[72:75], v[122:125]
	s_waitcnt lgkmcnt(4)
	v_mfma_f32_16x16x32_bf16 v[118:121], v[208:211], v[68:71], v[118:121]
	v_mfma_f32_16x16x32_bf16 v[102:105], v[208:211], v[76:79], v[102:105]
	ds_read_b128 v[204:207], v101 offset:34816
	ds_read_b128 v[208:211], v101 offset:35840
	s_waitcnt lgkmcnt(5)
	v_mfma_f32_16x16x32_bf16 v[126:129], v[212:215], v[64:67], v[126:129]
	v_mfma_f32_16x16x32_bf16 v[84:87], v[212:215], v[72:75], v[130:133]
	s_waitcnt lgkmcnt(4)
	v_mfma_f32_16x16x32_bf16 v[126:129], v[216:219], v[68:71], v[126:129]
	v_mfma_f32_16x16x32_bf16 v[84:87], v[216:219], v[76:79], v[84:87]
	ds_read_b128 v[212:215], v101 offset:36864
	ds_read_b128 v[216:219], v101 offset:37888
	s_waitcnt lgkmcnt(5)
	v_mfma_f32_16x16x32_bf16 v[0:3], v[220:223], v[64:67], v[0:3]
	v_mfma_f32_16x16x32_bf16 v[114:117], v[220:223], v[72:75], v[20:23]
	s_waitcnt lgkmcnt(4)
	v_mfma_f32_16x16x32_bf16 v[20:23], v[234:237], v[68:71], v[0:3]
	v_mfma_f32_16x16x32_bf16 v[0:3], v[234:237], v[76:79], v[114:117]
	ds_read_b128 v[220:223], v101 offset:38912
	ds_read_b128 v[234:237], v101 offset:39936
	s_waitcnt lgkmcnt(5)
	v_mfma_f32_16x16x32_bf16 v[4:7], v[204:207], v[64:67], v[4:7]
	v_mfma_f32_16x16x32_bf16 v[110:113], v[204:207], v[72:75], v[28:31]
	s_waitcnt lgkmcnt(4)
	v_mfma_f32_16x16x32_bf16 v[28:31], v[208:211], v[68:71], v[4:7]
	v_mfma_f32_16x16x32_bf16 v[4:7], v[208:211], v[76:79], v[110:113]
	ds_read_b128 v[204:207], v101 offset:40960
	ds_read_b128 v[208:211], v101 offset:41984
	s_waitcnt lgkmcnt(5)
	v_mfma_f32_16x16x32_bf16 v[8:11], v[212:215], v[64:67], v[8:11]
	v_mfma_f32_16x16x32_bf16 v[114:117], v[212:215], v[72:75], v[36:39]
	s_waitcnt lgkmcnt(4)
	v_mfma_f32_16x16x32_bf16 v[36:39], v[216:219], v[68:71], v[8:11]
	v_mfma_f32_16x16x32_bf16 v[8:11], v[216:219], v[76:79], v[114:117]
	ds_read_b128 v[212:215], v101 offset:43008
	ds_read_b128 v[216:219], v101 offset:44032
	s_waitcnt lgkmcnt(5)
	v_mfma_f32_16x16x32_bf16 v[12:15], v[220:223], v[64:67], v[12:15]
	v_mfma_f32_16x16x32_bf16 v[110:113], v[220:223], v[72:75], v[44:47]
	s_waitcnt lgkmcnt(4)
	v_mfma_f32_16x16x32_bf16 v[44:47], v[234:237], v[68:71], v[12:15]
	v_mfma_f32_16x16x32_bf16 v[12:15], v[234:237], v[76:79], v[110:113]
	ds_read_b128 v[220:223], v101 offset:45056
	ds_read_b128 v[234:237], v101 offset:46080
	s_waitcnt lgkmcnt(5)
	v_mfma_f32_16x16x32_bf16 v[16:19], v[204:207], v[64:67], v[16:19]
	v_mfma_f32_16x16x32_bf16 v[114:117], v[204:207], v[72:75], v[48:51]
	s_waitcnt lgkmcnt(4)
	v_mfma_f32_16x16x32_bf16 v[48:51], v[208:211], v[68:71], v[16:19]
	v_mfma_f32_16x16x32_bf16 v[16:19], v[208:211], v[76:79], v[114:117]
	ds_read_b128 v[204:207], v101 offset:47104
	ds_read_b128 v[208:211], v101 offset:48128
	s_waitcnt lgkmcnt(5)
	v_mfma_f32_16x16x32_bf16 v[24:27], v[212:215], v[64:67], v[24:27]
	v_mfma_f32_16x16x32_bf16 v[110:113], v[212:215], v[72:75], v[52:55]
	s_waitcnt lgkmcnt(4)
	v_mfma_f32_16x16x32_bf16 v[52:55], v[216:219], v[68:71], v[24:27]
	v_mfma_f32_16x16x32_bf16 v[24:27], v[216:219], v[76:79], v[110:113]
	s_waitcnt lgkmcnt(3)
	v_mfma_f32_16x16x32_bf16 v[32:35], v[220:223], v[64:67], v[32:35]
	v_mfma_f32_16x16x32_bf16 v[114:117], v[220:223], v[72:75], v[56:59]
	s_waitcnt lgkmcnt(2)
	v_mfma_f32_16x16x32_bf16 v[56:59], v[234:237], v[68:71], v[32:35]
	v_mfma_f32_16x16x32_bf16 v[32:35], v[234:237], v[76:79], v[114:117]
	s_waitcnt lgkmcnt(1)
	v_mfma_f32_16x16x32_bf16 v[40:43], v[204:207], v[64:67], v[40:43]
	v_mfma_f32_16x16x32_bf16 v[64:67], v[204:207], v[72:75], v[60:63]
	s_waitcnt lgkmcnt(0)
	v_mfma_f32_16x16x32_bf16 v[60:63], v[208:211], v[68:71], v[40:43]
	v_mfma_f32_16x16x32_bf16 v[40:43], v[208:211], v[76:79], v[64:67]
	s_add_i32 s36, s1, 2
	s_cmp_lt_u32 s1, 62
	s_cselect_b32 s0, s36, s2
	s_lshl_b32 s0, s0, 14
	s_add_u32 s38, s40, s0
	s_waitcnt lgkmcnt(0)
	s_barrier
	ds_write_b32 v201, v88
	ds_write_b32 v201, v89 offset:528
	ds_write_b32 v201, v90 offset:1056
	ds_write_b32 v202, v91
	ds_write_b32 v201, v106 offset:8448
	ds_write_b32 v201, v107 offset:8976
	ds_write_b32 v201, v108 offset:9504
	ds_write_b32 v201, v109 offset:10032
	ds_write_b32 v201, v118 offset:16896
	ds_write_b32 v201, v119 offset:17424
	ds_write_b32 v201, v120 offset:17952
	ds_write_b32 v201, v121 offset:18480
	ds_write_b32 v201, v126 offset:25344
	ds_write_b32 v201, v127 offset:25872
	ds_write_b32 v201, v128 offset:26400
	ds_write_b32 v201, v129 offset:26928
	ds_write_b32 v201, v92 offset:64
	ds_write_b32 v201, v93 offset:592
	ds_write_b32 v201, v94 offset:1120
	ds_write_b32 v202, v95 offset:64
	ds_write_b32 v201, v80 offset:8512
	ds_write_b32 v201, v81 offset:9040
	ds_write_b32 v201, v82 offset:9568
	ds_write_b32 v201, v83 offset:10096
	ds_write_b32 v201, v102 offset:16960
	ds_write_b32 v201, v103 offset:17488
	ds_write_b32 v201, v104 offset:18016
	ds_write_b32 v201, v105 offset:18544
	ds_write_b32 v201, v84 offset:25408
	ds_write_b32 v201, v85 offset:25936
	ds_write_b32 v201, v86 offset:26464
	ds_write_b32 v201, v87 offset:26992
	s_addc_u32 s39, s41, 0
	s_waitcnt lgkmcnt(0)
	s_barrier
	v_lshl_add_u64 v[64:65], s[38:39], 0, v[98:99]
	v_lshl_add_u64 v[66:67], s[38:39], 0, v[134:135]
	v_lshl_add_u64 v[68:69], s[38:39], 0, v[136:137]
	v_lshl_add_u64 v[70:71], s[38:39], 0, v[138:139]
	global_load_dwordx2 v[178:179], v[64:65], off
	global_load_dwordx2 v[174:175], v[66:67], off
	global_load_dwordx2 v[170:171], v[68:69], off
	global_load_dwordx2 v[164:165], v[70:71], off
	v_lshl_add_u64 v[64:65], s[38:39], 0, v[140:141]
	v_lshl_add_u64 v[66:67], s[38:39], 0, v[142:143]
	v_lshl_add_u64 v[68:69], s[38:39], 0, v[144:145]
	v_lshl_add_u64 v[70:71], s[38:39], 0, v[146:147]
	global_load_dwordx2 v[176:177], v[64:65], off
	global_load_dwordx2 v[172:173], v[66:67], off
	global_load_dwordx2 v[168:169], v[68:69], off
	global_load_dwordx2 v[166:167], v[70:71], off
	s_add_u32 s30, s30, 0x8000
	s_addc_u32 s31, s31, 0
	s_cmp_gt_u32 s1, 61
	ds_read_b128 v[88:91], v200 offset:16384
	ds_read_b128 v[92:95], v200 offset:17408
	ds_read_b128 v[106:109], v200 offset:18432
	ds_read_b128 v[110:113], v200 offset:19456
	ds_read_b128 v[118:121], v200 offset:20480
	ds_read_b128 v[122:125], v200 offset:21504
	ds_read_b128 v[126:129], v200 offset:22528
	ds_read_b128 v[130:133], v200 offset:23552
	v_cvt_pk_bf16_f32 v64, v20, v21
	v_cvt_pk_bf16_f32 v65, v22, v23
	v_cvt_pk_bf16_f32 v66, v28, v29
	v_cvt_pk_bf16_f32 v67, v30, v31
	v_cvt_pk_bf16_f32 v68, v36, v37
	v_cvt_pk_bf16_f32 v69, v38, v39
	v_cvt_pk_bf16_f32 v70, v44, v45
	v_cvt_pk_bf16_f32 v71, v46, v47
	v_cvt_pk_bf16_f32 v72, v48, v49
	v_cvt_pk_bf16_f32 v73, v50, v51
	v_cvt_pk_bf16_f32 v74, v52, v53
	v_cvt_pk_bf16_f32 v75, v54, v55
	v_cvt_pk_bf16_f32 v76, v56, v57
	v_cvt_pk_bf16_f32 v77, v58, v59
	v_cvt_pk_bf16_f32 v78, v60, v61
	v_cvt_pk_bf16_f32 v79, v62, v63
	v_cvt_pk_bf16_f32 v84, v0, v1
	v_cvt_pk_bf16_f32 v85, v2, v3
	v_cvt_pk_bf16_f32 v86, v4, v5
	v_cvt_pk_bf16_f32 v87, v6, v7
	v_cvt_pk_bf16_f32 v80, v8, v9
	v_cvt_pk_bf16_f32 v81, v10, v11
	v_cvt_pk_bf16_f32 v82, v12, v13
	v_cvt_pk_bf16_f32 v83, v14, v15
	v_cvt_pk_bf16_f32 v102, v16, v17
	v_cvt_pk_bf16_f32 v103, v18, v19
	v_cvt_pk_bf16_f32 v104, v24, v25
	v_cvt_pk_bf16_f32 v105, v26, v27
	v_cvt_pk_bf16_f32 v114, v32, v33
	v_cvt_pk_bf16_f32 v115, v34, v35
	v_cvt_pk_bf16_f32 v116, v40, v41
	v_cvt_pk_bf16_f32 v117, v42, v43
	v_readlane_b32 s0, v96, s2
	s_waitcnt lgkmcnt(7)
	v_mfma_f32_16x16x32_bf16 v[204:207], v[88:91], v[64:67], 0
	v_mfma_f32_16x16x32_bf16 v[88:91], v[88:91], v[84:87], 0
	s_waitcnt lgkmcnt(6)
	v_mfma_f32_16x16x32_bf16 v[204:207], v[92:95], v[68:71], v[204:207]
	v_mfma_f32_16x16x32_bf16 v[88:91], v[92:95], v[80:83], v[88:91]
	s_waitcnt lgkmcnt(5)
	v_mfma_f32_16x16x32_bf16 v[92:95], v[106:109], v[72:75], v[204:207]
	v_mfma_f32_16x16x32_bf16 v[106:109], v[106:109], v[102:105], v[88:91]
	s_waitcnt lgkmcnt(4)
	v_mfma_f32_16x16x32_bf16 v[88:91], v[110:113], v[76:79], v[92:95]
	v_mfma_f32_16x16x32_bf16 v[92:95], v[110:113], v[114:117], v[106:109]
	v_pk_mul_f32 v[22:23], v[22:23], s[0:1] op_sel_hi:[1,0]
	v_pk_mul_f32 v[20:21], v[20:21], s[0:1] op_sel_hi:[1,0]
	v_pk_mul_f32 v[2:3], v[2:3], s[0:1] op_sel_hi:[1,0]
	v_pk_mul_f32 v[0:1], v[0:1], s[0:1] op_sel_hi:[1,0]
	v_pk_mul_f32 v[30:31], v[30:31], s[0:1] op_sel_hi:[1,0]
	s_nop 0
	ds_read_b128 v[204:207], v200 offset:24576
	ds_read_b128 v[208:211], v200 offset:25600
	ds_read_b128 v[212:215], v200 offset:26624
	ds_read_b128 v[216:219], v200 offset:27648
	s_waitcnt lgkmcnt(7)
	v_mfma_f32_16x16x32_bf16 v[106:109], v[118:121], v[64:67], 0
	v_mfma_f32_16x16x32_bf16 v[110:113], v[118:121], v[84:87], 0
	s_waitcnt lgkmcnt(6)
	v_mfma_f32_16x16x32_bf16 v[106:109], v[122:125], v[68:71], v[106:109]
	v_mfma_f32_16x16x32_bf16 v[110:113], v[122:125], v[80:83], v[110:113]
	s_waitcnt lgkmcnt(5)
	v_mfma_f32_16x16x32_bf16 v[106:109], v[126:129], v[72:75], v[106:109]
	v_mfma_f32_16x16x32_bf16 v[110:113], v[126:129], v[102:105], v[110:113]
	s_waitcnt lgkmcnt(4)
	v_mfma_f32_16x16x32_bf16 v[106:109], v[130:133], v[76:79], v[106:109]
	v_mfma_f32_16x16x32_bf16 v[110:113], v[130:133], v[114:117], v[110:113]
	v_pk_mul_f32 v[28:29], v[28:29], s[0:1] op_sel_hi:[1,0]
	v_pk_mul_f32 v[6:7], v[6:7], s[0:1] op_sel_hi:[1,0]
	v_pk_mul_f32 v[4:5], v[4:5], s[0:1] op_sel_hi:[1,0]
	v_pk_mul_f32 v[38:39], v[38:39], s[0:1] op_sel_hi:[1,0]
	ds_read_b128 v[126:129], v200 offset:28672
	ds_read_b128 v[130:133], v200 offset:29696
	ds_read_b128 v[220:223], v200 offset:30720
	ds_read_b128 v[234:237], v200 offset:31744
	s_waitcnt lgkmcnt(7)
	v_mfma_f32_16x16x32_bf16 v[118:121], v[204:207], v[64:67], 0
	v_mfma_f32_16x16x32_bf16 v[122:125], v[204:207], v[84:87], 0
	s_waitcnt lgkmcnt(6)
	v_mfma_f32_16x16x32_bf16 v[118:121], v[208:211], v[68:71], v[118:121]
	v_mfma_f32_16x16x32_bf16 v[122:125], v[208:211], v[80:83], v[122:125]
	s_waitcnt lgkmcnt(5)
	v_mfma_f32_16x16x32_bf16 v[118:121], v[212:215], v[72:75], v[118:121]
	v_mfma_f32_16x16x32_bf16 v[122:125], v[212:215], v[102:105], v[122:125]
	s_waitcnt lgkmcnt(4)
	v_mfma_f32_16x16x32_bf16 v[118:121], v[216:219], v[76:79], v[118:121]
	v_mfma_f32_16x16x32_bf16 v[122:125], v[216:219], v[114:117], v[122:125]
	v_pk_mul_f32 v[36:37], v[36:37], s[0:1] op_sel_hi:[1,0]
	v_pk_mul_f32 v[10:11], v[10:11], s[0:1] op_sel_hi:[1,0]
	v_pk_mul_f32 v[8:9], v[8:9], s[0:1] op_sel_hi:[1,0]
	v_pk_mul_f32 v[46:47], v[46:47], s[0:1] op_sel_hi:[1,0]
	ds_read_b128 v[204:207], v101 offset:57344
	ds_read_b128 v[208:211], v101 offset:58368
	ds_read_b128 v[212:215], v101 offset:59392
	ds_read_b128 v[216:219], v101 offset:60416
	s_waitcnt lgkmcnt(7)
	v_mfma_f32_16x16x32_bf16 v[238:241], v[126:129], v[64:67], 0
	v_mfma_f32_16x16x32_bf16 v[126:129], v[126:129], v[84:87], 0
	s_waitcnt lgkmcnt(6)
	v_mfma_f32_16x16x32_bf16 v[238:241], v[130:133], v[68:71], v[238:241]
	v_mfma_f32_16x16x32_bf16 v[126:129], v[130:133], v[80:83], v[126:129]
	s_waitcnt lgkmcnt(5)
	v_mfma_f32_16x16x32_bf16 v[130:133], v[220:223], v[72:75], v[238:241]
	v_mfma_f32_16x16x32_bf16 v[220:223], v[220:223], v[102:105], v[126:129]
	s_waitcnt lgkmcnt(4)
	v_mfma_f32_16x16x32_bf16 v[126:129], v[234:237], v[76:79], v[130:133]
	v_mfma_f32_16x16x32_bf16 v[130:133], v[234:237], v[114:117], v[220:223]
	v_pk_mul_f32 v[44:45], v[44:45], s[0:1] op_sel_hi:[1,0]
	v_pk_mul_f32 v[14:15], v[14:15], s[0:1] op_sel_hi:[1,0]
	v_pk_mul_f32 v[12:13], v[12:13], s[0:1] op_sel_hi:[1,0]
	v_pk_mul_f32 v[50:51], v[50:51], s[0:1] op_sel_hi:[1,0]
	s_nop 4
	ds_read_b128 v[220:223], v101 offset:61440
	ds_read_b128 v[234:237], v101 offset:62464
	ds_read_b128 v[238:241], v101 offset:63488
	ds_read_b128 v[242:245], v101 offset:64512
	s_waitcnt lgkmcnt(7)
	v_mfma_f32_16x16x32_bf16 v[246:249], v[204:207], v[64:67], 0
	s_waitcnt vmcnt(15)
	v_lshlrev_b32_e32 v182, 16, v198
	v_and_b32_e32 v183, 0xffff0000, v198
	v_lshlrev_b32_e32 v198, 16, v199
	v_mfma_f32_16x16x32_bf16 v[204:207], v[204:207], v[84:87], 0
	v_and_b32_e32 v199, 0xffff0000, v199
	s_waitcnt lgkmcnt(6)
	v_mfma_f32_16x16x32_bf16 v[246:249], v[208:211], v[68:71], v[246:249]
	v_mfma_f32_16x16x32_bf16 v[204:207], v[208:211], v[80:83], v[204:207]
	s_waitcnt lgkmcnt(5)
	v_mfma_f32_16x16x32_bf16 v[208:211], v[212:215], v[72:75], v[246:249]
	v_mfma_f32_16x16x32_bf16 v[204:207], v[212:215], v[102:105], v[204:207]
	s_waitcnt lgkmcnt(4)
	v_mfma_f32_16x16x32_bf16 v[208:211], v[216:219], v[76:79], v[208:211]
	v_mfma_f32_16x16x32_bf16 v[204:207], v[216:219], v[114:117], v[204:207]
	v_pk_mul_f32 v[48:49], v[48:49], s[0:1] op_sel_hi:[1,0]
	v_pk_mul_f32 v[18:19], v[18:19], s[0:1] op_sel_hi:[1,0]
	v_pk_mul_f32 v[16:17], v[16:17], s[0:1] op_sel_hi:[1,0]
	v_pk_mul_f32 v[54:55], v[54:55], s[0:1] op_sel_hi:[1,0]
	s_nop 6
	v_sub_f32_e32 v203, v199, v211
	v_sub_f32_e32 v224, v198, v210
	s_waitcnt vmcnt(11)
	v_lshlrev_b32_e32 v198, 16, v196
	v_and_b32_e32 v196, 0xffff0000, v196
	v_lshlrev_b32_e32 v199, 16, v197
	v_and_b32_e32 v197, 0xffff0000, v197
	v_sub_f32_e32 v183, v183, v209
	v_sub_f32_e32 v182, v182, v208
	v_sub_f32_e32 v225, v197, v207
	v_sub_f32_e32 v227, v199, v206
	v_sub_f32_e32 v233, v196, v205
	v_sub_f32_e32 v246, v198, v204
	ds_read_b128 v[196:199], v200 offset:8192
	ds_read_b128 v[204:207], v200 offset:9216
	ds_read_b128 v[208:211], v200 offset:10240
	ds_read_b128 v[212:215], v200 offset:11264
	s_waitcnt lgkmcnt(7)
	v_mfma_f32_16x16x32_bf16 v[216:219], v[220:223], v[64:67], 0
	v_mfma_f32_16x16x32_bf16 v[220:223], v[220:223], v[84:87], 0
	s_waitcnt lgkmcnt(6)
	v_mfma_f32_16x16x32_bf16 v[216:219], v[234:237], v[68:71], v[216:219]
	v_mfma_f32_16x16x32_bf16 v[220:223], v[234:237], v[80:83], v[220:223]
	v_lshlrev_b32_e32 v234, 16, v194
	v_and_b32_e32 v194, 0xffff0000, v194
	v_lshlrev_b32_e32 v235, 16, v195
	s_waitcnt lgkmcnt(5)
	v_mfma_f32_16x16x32_bf16 v[216:219], v[238:241], v[72:75], v[216:219]
	v_and_b32_e32 v195, 0xffff0000, v195
	v_mfma_f32_16x16x32_bf16 v[220:223], v[238:241], v[102:105], v[220:223]
	s_waitcnt lgkmcnt(4)
	v_mfma_f32_16x16x32_bf16 v[216:219], v[242:245], v[76:79], v[216:219]
	v_mfma_f32_16x16x32_bf16 v[220:223], v[242:245], v[114:117], v[220:223]
	v_pk_mul_f32 v[52:53], v[52:53], s[0:1] op_sel_hi:[1,0]
	v_pk_mul_f32 v[26:27], v[26:27], s[0:1] op_sel_hi:[1,0]
	v_pk_mul_f32 v[24:25], v[24:25], s[0:1] op_sel_hi:[1,0]
	v_pk_mul_f32 v[58:59], v[58:59], s[0:1] op_sel_hi:[1,0]
	s_nop 6
	v_sub_f32_e32 v242, v195, v219
	v_sub_f32_e32 v244, v194, v217
	s_waitcnt vmcnt(10)
	v_lshlrev_b32_e32 v194, 16, v192
	v_and_b32_e32 v192, 0xffff0000, v192
	v_lshlrev_b32_e32 v195, 16, v193
	v_and_b32_e32 v193, 0xffff0000, v193
	v_sub_f32_e32 v243, v235, v218
	v_sub_f32_e32 v245, v234, v216
	v_sub_f32_e32 v247, v193, v223
	v_sub_f32_e32 v248, v195, v222
	v_sub_f32_e32 v249, v192, v221
	v_sub_f32_e32 v250, v194, v220
	ds_read_b128 v[192:195], v200 offset:12288
	ds_read_b128 v[216:219], v200 offset:13312
	ds_read_b128 v[220:223], v200 offset:14336
	ds_read_b128 v[234:237], v200 offset:15360
	s_waitcnt lgkmcnt(7)
	v_mfma_f32_16x16x32_bf16 v[238:241], v[196:199], v[64:67], 0
	v_mfma_f32_16x16x32_bf16 v[196:199], v[196:199], v[84:87], 0
	s_waitcnt lgkmcnt(6)
	v_mfma_f32_16x16x32_bf16 v[238:241], v[204:207], v[68:71], v[238:241]
	v_mfma_f32_16x16x32_bf16 v[196:199], v[204:207], v[80:83], v[196:199]
	s_waitcnt lgkmcnt(5)
	v_mfma_f32_16x16x32_bf16 v[204:207], v[208:211], v[72:75], v[238:241]
	v_mfma_f32_16x16x32_bf16 v[196:199], v[208:211], v[102:105], v[196:199]
	v_lshlrev_b32_e32 v208, 16, v190
	v_and_b32_e32 v190, 0xffff0000, v190
	v_lshlrev_b32_e32 v209, 16, v191
	s_waitcnt lgkmcnt(4)
	v_mfma_f32_16x16x32_bf16 v[204:207], v[212:215], v[76:79], v[204:207]
	v_and_b32_e32 v191, 0xffff0000, v191
	v_mfma_f32_16x16x32_bf16 v[196:199], v[212:215], v[114:117], v[196:199]
	v_pk_mul_f32 v[56:57], v[56:57], s[0:1] op_sel_hi:[1,0]
	v_pk_mul_f32 v[34:35], v[34:35], s[0:1] op_sel_hi:[1,0]
	v_pk_mul_f32 v[32:33], v[32:33], s[0:1] op_sel_hi:[1,0]
	v_mul_f32_e64 v62, v62, s0
	s_nop 5
	v_sub_f32_e32 v207, v191, v207
	v_sub_f32_e32 v205, v190, v205
	s_waitcnt vmcnt(9)
	v_lshlrev_b32_e32 v190, 16, v188
	v_and_b32_e32 v188, 0xffff0000, v188
	v_lshlrev_b32_e32 v191, 16, v189
	v_and_b32_e32 v189, 0xffff0000, v189
	v_sub_f32_e32 v206, v209, v206
	v_sub_f32_e32 v204, v208, v204
	v_sub_f32_e32 v208, v189, v199
	v_sub_f32_e32 v209, v191, v198
	v_sub_f32_e32 v210, v188, v197
	v_sub_f32_e32 v211, v190, v196
	ds_read_b128 v[188:191], v200 offset:49152
	ds_read_b128 v[196:199], v200 offset:50176
	s_waitcnt lgkmcnt(5)
	v_mfma_f32_16x16x32_bf16 v[64:67], v[192:195], v[64:67], 0
	s_waitcnt lgkmcnt(4)
	v_mfma_f32_16x16x32_bf16 v[64:67], v[216:219], v[68:71], v[64:67]
	v_lshlrev_b32_e32 v68, 16, v181
	v_and_b32_e32 v69, 0xffff0000, v181
	v_lshlrev_b32_e32 v70, 16, v180
	s_waitcnt lgkmcnt(3)
	v_mfma_f32_16x16x32_bf16 v[64:67], v[220:223], v[72:75], v[64:67]
	v_and_b32_e32 v71, 0xffff0000, v180
	s_waitcnt vmcnt(8)
	v_lshlrev_b32_e32 v74, 16, v186
	v_and_b32_e32 v75, 0xffff0000, v187
	v_mfma_f32_16x16x32_bf16 v[84:87], v[192:195], v[84:87], 0
	s_waitcnt lgkmcnt(2)
	v_mfma_f32_16x16x32_bf16 v[64:67], v[234:237], v[76:79], v[64:67]
	v_cvt_pk_bf16_f32 v76, v211, v210
	v_cvt_pk_bf16_f32 v77, v209, v208
	s_nop 5
	v_sub_f32_e32 v72, v69, v67
	v_sub_f32_e32 v73, v68, v66
	v_mfma_f32_16x16x32_bf16 v[66:69], v[216:219], v[80:83], v[84:87]
	v_sub_f32_e32 v71, v71, v65
	v_sub_f32_e32 v70, v70, v64
	v_cvt_pk_bf16_f32 v70, v70, v71
	v_mfma_f32_16x16x32_bf16 v[64:67], v[220:223], v[102:105], v[66:69]
	v_cvt_pk_bf16_f32 v71, v73, v72
	v_cvt_pk_bf16_f32 v72, v246, v233
	v_cvt_pk_bf16_f32 v73, v227, v225
	v_mfma_f32_16x16x32_bf16 v[64:67], v[234:237], v[114:117], v[64:67]
	v_mul_f32_e64 v63, v63, s0
	v_pk_mul_f32 v[60:61], v[60:61], s[0:1] op_sel_hi:[1,0]
	v_pk_mul_f32 v[42:43], v[42:43], s[0:1] op_sel_hi:[1,0]
	v_pk_mul_f32 v[40:41], v[40:41], s[0:1] op_sel_hi:[1,0]
	v_and_b32_e32 v68, 0xffff0000, v186
	v_lshlrev_b32_e32 v69, 16, v187
	s_nop 5
	v_sub_f32_e32 v79, v75, v67
	v_sub_f32_e32 v80, v69, v66
	v_sub_f32_e32 v78, v68, v65
	v_sub_f32_e32 v81, v74, v64
	v_cvt_pk_bf16_f32 v64, v182, v183
	v_cvt_pk_bf16_f32 v65, v224, v203
	v_cvt_pk_bf16_f32 v66, v245, v244
	v_cvt_pk_bf16_f32 v67, v243, v242
	v_cvt_pk_bf16_f32 v68, v204, v205
	v_cvt_pk_bf16_f32 v69, v206, v207
	v_cvt_pk_bf16_f32 v74, v250, v249
	v_cvt_pk_bf16_f32 v75, v248, v247
	v_cvt_pk_bf16_f32 v78, v81, v78
	v_cvt_pk_bf16_f32 v79, v80, v79
	ds_read_b128 v[80:83], v200 offset:51200
	ds_read_b128 v[84:87], v200 offset:52224
	ds_read_b128 v[204:207], v200 offset:53248
	ds_read_b128 v[208:211], v200 offset:54272
	s_waitcnt lgkmcnt(5)
	v_mfma_f32_16x16x32_bf16 v[88:91], v[188:191], v[64:67], v[88:91]
	v_mfma_f32_16x16x32_bf16 v[92:95], v[188:191], v[72:75], v[92:95]
	s_waitcnt lgkmcnt(4)
	v_mfma_f32_16x16x32_bf16 v[88:91], v[196:199], v[68:71], v[88:91]
	v_mfma_f32_16x16x32_bf16 v[92:95], v[196:199], v[76:79], v[92:95]
	ds_read_b128 v[212:215], v200 offset:55296
	ds_read_b128 v[216:219], v200 offset:56320
	s_waitcnt lgkmcnt(5)
	v_mfma_f32_16x16x32_bf16 v[106:109], v[80:83], v[64:67], v[106:109]
	v_mfma_f32_16x16x32_bf16 v[80:83], v[80:83], v[72:75], v[110:113]
	s_waitcnt lgkmcnt(4)
	v_mfma_f32_16x16x32_bf16 v[106:109], v[84:87], v[68:71], v[106:109]
	v_mfma_f32_16x16x32_bf16 v[80:83], v[84:87], v[76:79], v[80:83]
	ds_read_b128 v[220:223], v200 offset:32768
	ds_read_b128 v[234:237], v200 offset:33792
	s_waitcnt lgkmcnt(5)
	v_mfma_f32_16x16x32_bf16 v[118:121], v[204:207], v[64:67], v[118:121]
	v_mfma_f32_16x16x32_bf16 v[102:105], v[204:207], v[72:75], v[122:125]
	s_waitcnt lgkmcnt(4)
	v_mfma_f32_16x16x32_bf16 v[118:121], v[208:211], v[68:71], v[118:121]
	v_mfma_f32_16x16x32_bf16 v[102:105], v[208:211], v[76:79], v[102:105]
	ds_read_b128 v[204:207], v200 offset:34816
	ds_read_b128 v[208:211], v200 offset:35840
	s_waitcnt lgkmcnt(5)
	v_mfma_f32_16x16x32_bf16 v[126:129], v[212:215], v[64:67], v[126:129]
	v_mfma_f32_16x16x32_bf16 v[84:87], v[212:215], v[72:75], v[130:133]
	s_waitcnt lgkmcnt(4)
	v_mfma_f32_16x16x32_bf16 v[126:129], v[216:219], v[68:71], v[126:129]
	v_mfma_f32_16x16x32_bf16 v[84:87], v[216:219], v[76:79], v[84:87]
	ds_read_b128 v[212:215], v200 offset:36864
	ds_read_b128 v[216:219], v200 offset:37888
	s_waitcnt lgkmcnt(5)
	v_mfma_f32_16x16x32_bf16 v[20:23], v[220:223], v[64:67], v[20:23]
	v_mfma_f32_16x16x32_bf16 v[114:117], v[220:223], v[72:75], v[0:3]
	s_waitcnt lgkmcnt(4)
	v_mfma_f32_16x16x32_bf16 v[0:3], v[234:237], v[68:71], v[20:23]
	v_mfma_f32_16x16x32_bf16 v[20:23], v[234:237], v[76:79], v[114:117]
	ds_read_b128 v[220:223], v200 offset:38912
	ds_read_b128 v[234:237], v200 offset:39936
	s_waitcnt lgkmcnt(5)
	v_mfma_f32_16x16x32_bf16 v[28:31], v[204:207], v[64:67], v[28:31]
	v_mfma_f32_16x16x32_bf16 v[110:113], v[204:207], v[72:75], v[4:7]
	s_waitcnt lgkmcnt(4)
	v_mfma_f32_16x16x32_bf16 v[4:7], v[208:211], v[68:71], v[28:31]
	v_mfma_f32_16x16x32_bf16 v[28:31], v[208:211], v[76:79], v[110:113]
	ds_read_b128 v[204:207], v200 offset:40960
	ds_read_b128 v[208:211], v200 offset:41984
	s_waitcnt lgkmcnt(5)
	v_mfma_f32_16x16x32_bf16 v[36:39], v[212:215], v[64:67], v[36:39]
	v_mfma_f32_16x16x32_bf16 v[114:117], v[212:215], v[72:75], v[8:11]
	s_waitcnt lgkmcnt(4)
	v_mfma_f32_16x16x32_bf16 v[8:11], v[216:219], v[68:71], v[36:39]
	v_mfma_f32_16x16x32_bf16 v[36:39], v[216:219], v[76:79], v[114:117]
	ds_read_b128 v[212:215], v200 offset:43008
	ds_read_b128 v[216:219], v200 offset:44032
	s_waitcnt lgkmcnt(5)
	v_mfma_f32_16x16x32_bf16 v[44:47], v[220:223], v[64:67], v[44:47]
	v_mfma_f32_16x16x32_bf16 v[110:113], v[220:223], v[72:75], v[12:15]
	s_waitcnt lgkmcnt(4)
	v_mfma_f32_16x16x32_bf16 v[12:15], v[234:237], v[68:71], v[44:47]
	v_mfma_f32_16x16x32_bf16 v[44:47], v[234:237], v[76:79], v[110:113]
	ds_read_b128 v[220:223], v200 offset:45056
	ds_read_b128 v[234:237], v200 offset:46080
	s_waitcnt lgkmcnt(5)
	v_mfma_f32_16x16x32_bf16 v[48:51], v[204:207], v[64:67], v[48:51]
	v_mfma_f32_16x16x32_bf16 v[114:117], v[204:207], v[72:75], v[16:19]
	s_waitcnt lgkmcnt(4)
	v_mfma_f32_16x16x32_bf16 v[16:19], v[208:211], v[68:71], v[48:51]
	v_mfma_f32_16x16x32_bf16 v[48:51], v[208:211], v[76:79], v[114:117]
	ds_read_b128 v[204:207], v200 offset:47104
	ds_read_b128 v[208:211], v200 offset:48128
	s_waitcnt lgkmcnt(5)
	v_mfma_f32_16x16x32_bf16 v[52:55], v[212:215], v[64:67], v[52:55]
	v_mfma_f32_16x16x32_bf16 v[110:113], v[212:215], v[72:75], v[24:27]
	s_waitcnt lgkmcnt(4)
	v_mfma_f32_16x16x32_bf16 v[24:27], v[216:219], v[68:71], v[52:55]
	v_mfma_f32_16x16x32_bf16 v[52:55], v[216:219], v[76:79], v[110:113]
	s_waitcnt lgkmcnt(3)
	v_mfma_f32_16x16x32_bf16 v[56:59], v[220:223], v[64:67], v[56:59]
	v_mfma_f32_16x16x32_bf16 v[114:117], v[220:223], v[72:75], v[32:35]
	s_waitcnt lgkmcnt(2)
	v_mfma_f32_16x16x32_bf16 v[32:35], v[234:237], v[68:71], v[56:59]
	v_mfma_f32_16x16x32_bf16 v[56:59], v[234:237], v[76:79], v[114:117]
	s_waitcnt lgkmcnt(1)
	v_mfma_f32_16x16x32_bf16 v[60:63], v[204:207], v[64:67], v[60:63]
	v_mfma_f32_16x16x32_bf16 v[64:67], v[204:207], v[72:75], v[40:43]
	s_waitcnt lgkmcnt(0)
	v_mfma_f32_16x16x32_bf16 v[40:43], v[208:211], v[68:71], v[60:63]
	v_mfma_f32_16x16x32_bf16 v[60:63], v[208:211], v[76:79], v[64:67]
	s_waitcnt lgkmcnt(0)
	s_barrier
	ds_write_b32 v201, v88
	ds_write_b32 v201, v89 offset:528
	ds_write_b32 v201, v90 offset:1056
	ds_write_b32 v202, v91
	ds_write_b32 v201, v106 offset:8448
	ds_write_b32 v201, v107 offset:8976
	ds_write_b32 v201, v108 offset:9504
	ds_write_b32 v201, v109 offset:10032
	ds_write_b32 v201, v118 offset:16896
	ds_write_b32 v201, v119 offset:17424
	ds_write_b32 v201, v120 offset:17952
	ds_write_b32 v201, v121 offset:18480
	ds_write_b32 v201, v126 offset:25344
	ds_write_b32 v201, v127 offset:25872
	ds_write_b32 v201, v128 offset:26400
	ds_write_b32 v201, v129 offset:26928
	ds_write_b32 v201, v92 offset:64
	ds_write_b32 v201, v93 offset:592
	ds_write_b32 v201, v94 offset:1120
	ds_write_b32 v202, v95 offset:64
	ds_write_b32 v201, v80 offset:8512
	ds_write_b32 v201, v81 offset:9040
	ds_write_b32 v201, v82 offset:9568
	ds_write_b32 v201, v83 offset:10096
	ds_write_b32 v201, v102 offset:16960
	ds_write_b32 v201, v103 offset:17488
	ds_write_b32 v201, v104 offset:18016
	ds_write_b32 v201, v105 offset:18544
	ds_write_b32 v201, v84 offset:25408
	ds_write_b32 v201, v85 offset:25936
	ds_write_b32 v201, v86 offset:26464
	ds_write_b32 v201, v87 offset:26992
	s_waitcnt lgkmcnt(0)
	s_barrier
	s_mov_b32 s1, s36
	s_cbranch_scc0 .LBB0_988
	s_waitcnt lgkmcnt(0)
	s_barrier
	s_waitcnt lgkmcnt(0)
	s_barrier
	v_mov_b32_e32 v227, 1
	v_mov_b64_e32 v[244:245], 0x100
